# stack17 + final RMSNorm (P11): gain vector preloaded once, per-piece load and vmcnt(0) waits removed from the row loop
# speedup vs baseline: 1.0382x; 1.0109x over previous
.LBB0_1392:
	s_cmp_lt_i32 s92, 12
	s_cselect_b64 s[4:5], -1, 0
	s_and_b64 s[2:3], s[4:5], s[2:3]
	s_andn2_b64 vcc, exec, s[2:3]
	s_cbranch_vccnz .LBB0_1396
	s_mov_b32 s2, 0
	s_cmpk_gt_i32 s20, 0x3fff
	s_cbranch_scc1 .LBB0_1396
	v_mbcnt_lo_u32_b32 v0, -1, 0
	v_mbcnt_hi_u32_b32 v0, -1, v0
	v_and_b32_e32 v2, 64, v0
	v_add_u32_e32 v2, 64, v2
	v_xor_b32_e32 v3, 1, v0
	v_cmp_lt_i32_e32 vcc, v3, v2
	s_ashr_i32 s3, s2, 31
	s_add_u32 s4, s0, s2
	v_cndmask_b32_e32 v3, v0, v3, vcc
	v_lshlrev_b32_e32 v24, 2, v3
	v_xor_b32_e32 v3, 2, v0
	v_cmp_lt_i32_e32 vcc, v3, v2
	s_addc_u32 s5, s1, s3
	s_load_dwordx4 s[0:3], s[4:5], 0xb0
	v_cndmask_b32_e32 v3, v0, v3, vcc
	v_lshlrev_b32_e32 v25, 2, v3
	v_xor_b32_e32 v3, 4, v0
	v_cmp_lt_i32_e32 vcc, v3, v2
	v_and_b32_e32 v1, 63, v0
	s_ashr_i32 s21, s20, 31
	v_cndmask_b32_e32 v3, v0, v3, vcc
	v_lshlrev_b32_e32 v26, 2, v3
	v_xor_b32_e32 v3, 8, v0
	v_cmp_lt_i32_e32 vcc, v3, v2
	s_lshl_b64 s[4:5], s[20:21], 13
	s_waitcnt lgkmcnt(0)
	s_add_u32 s2, s2, s4
	v_cndmask_b32_e32 v3, v0, v3, vcc
	v_lshlrev_b32_e32 v27, 2, v3
	v_xor_b32_e32 v3, 16, v0
	v_cmp_lt_i32_e32 vcc, v3, v2
	s_addc_u32 s3, s3, s5
	s_ashr_i32 s23, s22, 31
	v_cndmask_b32_e32 v3, v0, v3, vcc
	v_lshlrev_b32_e32 v28, 2, v3
	v_xor_b32_e32 v3, 32, v0
	v_cmp_lt_i32_e32 vcc, v3, v2
	v_mov_b32_e32 v30, 0x358637bd
	s_mov_b32 s4, 0xf800000
	v_cndmask_b32_e32 v0, v0, v3, vcc
	v_lshlrev_b32_e32 v29, 2, v0
	v_lshlrev_b32_e32 v0, 4, v1
	v_mov_b32_e32 v1, 0
	v_lshl_add_u64 v[12:13], s[0:1], 0, v[0:1]
	s_mov_b64 s[0:1], 0x1000
	v_lshl_add_u64 v[14:15], v[12:13], 0, s[0:1]
	s_mov_b64 s[0:1], 0x1400
	v_lshl_add_u64 v[16:17], v[12:13], 0, s[0:1]
	s_mov_b64 s[0:1], 0x1800
	v_lshl_add_u64 v[18:19], v[12:13], 0, s[0:1]
	s_mov_b64 s[0:1], 0x1c00
	v_lshl_add_u64 v[0:1], s[2:3], 0, v[0:1]
	v_lshl_add_u64 v[20:21], v[12:13], 0, s[0:1]
	v_lshl_add_u64 v[22:23], v[0:1], 0, s[0:1]
	s_lshl_b64 s[2:3], s[22:23], 13
	v_mov_b32_e32 v31, 0x260
	global_load_dwordx4 v[88:91], v[12:13], off
	global_load_dwordx4 v[92:95], v[12:13], off offset:1024
	global_load_dwordx4 v[96:99], v[12:13], off offset:2048
	global_load_dwordx4 v[100:103], v[12:13], off offset:3072
	global_load_dwordx4 v[104:107], v[14:15], off
	global_load_dwordx4 v[108:111], v[16:17], off
	global_load_dwordx4 v[112:115], v[18:19], off
	global_load_dwordx4 v[116:119], v[20:21], off
.LBB0_1395:
	global_load_dwordx4 v[4:7], v[22:23], off offset:-3072
	global_load_dwordx4 v[8:11], v[22:23], off offset:-2048
	global_load_dwordx4 v[0:3], v[22:23], off
	global_load_dwordx4 v[32:35], v[22:23], off offset:-1024
	v_add_co_u32_e32 v56, vcc, 0xfffff000, v22
	s_add_i32 s20, s20, s22
	s_nop 0
	v_addc_co_u32_e32 v57, vcc, -1, v23, vcc
	global_load_dwordx4 v[36:39], v[56:57], off offset:-3072
	global_load_dwordx4 v[40:43], v[56:57], off offset:-2048
	global_load_dwordx4 v[44:47], v[56:57], off offset:-1024
	global_load_dwordx4 v[48:51], v[22:23], off offset:-4096
	s_cmpk_lt_i32 s20, 0x4000
	s_waitcnt vmcnt(0)
	v_mul_f32_e32 v81, v4, v4
	v_pk_mul_f32 v[58:59], v[10:11], v[10:11]
	v_pk_mul_f32 v[60:61], v[8:9], v[8:9]
	v_mul_f32_e32 v62, v33, v33
	v_mul_f32_e32 v64, v35, v35
	v_mul_f32_e32 v79, v2, v2
	v_mul_f32_e32 v87, v3, v3
	v_pk_mov_b32 v[66:67], v[60:61], v[58:59] op_sel:[1,0]
	v_mov_b32_e32 v61, v59
	v_pk_fma_f32 v[58:59], v[32:33], v[32:33], v[62:63] op_sel_hi:[1,1,0]
	v_pk_fma_f32 v[62:63], v[34:35], v[34:35], v[64:65] op_sel_hi:[1,1,0]
	v_mov_b32_e32 v68, v37
	v_mov_b32_e32 v69, v41
	v_mov_b32_e32 v72, v39
	v_mov_b32_e32 v73, v43
	v_mov_b32_e32 v64, v36
	v_mov_b32_e32 v65, v40
	v_mov_b32_e32 v70, v38
	v_mov_b32_e32 v71, v42
	v_pk_mul_f32 v[74:75], v[46:47], v[46:47]
	v_pk_mul_f32 v[76:77], v[44:45], v[44:45]
	v_pk_add_f32 v[60:61], v[66:67], v[60:61]
	v_mov_b32_e32 v59, v79
	v_mov_b32_e32 v63, v87
	v_pk_mul_f32 v[66:67], v[68:69], v[68:69]
	v_pk_mul_f32 v[68:69], v[72:73], v[72:73]
	v_pk_mov_b32 v[72:73], v[76:77], v[74:75] op_sel:[1,0]
	v_mov_b32_e32 v77, v75
	v_pk_add_f32 v[58:59], v[58:59], v[62:63]
	v_pk_fma_f32 v[62:63], v[64:65], v[64:65], v[66:67]
	v_pk_fma_f32 v[64:65], v[70:71], v[70:71], v[68:69]
	v_mul_f32_e32 v78, v49, v49
	v_mul_f32_e32 v80, v51, v51
	v_pk_add_f32 v[66:67], v[72:73], v[76:77]
	v_pk_add_f32 v[62:63], v[62:63], v[64:65]
	v_mul_f32_e32 v82, v5, v5
	v_mul_f32_e32 v83, v6, v6
	v_mul_f32_e32 v84, v7, v7
	v_pk_fma_f32 v[74:75], v[48:49], v[48:49], v[78:79] op_sel_hi:[1,1,0]
	v_pk_fma_f32 v[78:79], v[50:51], v[50:51], v[80:81] op_sel_hi:[1,1,0]
	v_pk_add_f32 v[64:65], v[66:67], v[66:67] op_sel:[0,1] op_sel_hi:[1,0]
	v_pk_add_f32 v[62:63], v[62:63], v[62:63] op_sel:[0,1] op_sel_hi:[1,0]
	v_mov_b32_e32 v75, v83
	v_mov_b32_e32 v79, v84
	v_mov_b32_e32 v65, v82
	v_mov_b32_e32 v63, v81
	v_pk_add_f32 v[66:67], v[74:75], v[78:79]
	v_pk_add_f32 v[62:63], v[62:63], v[64:65]
	v_mul_f32_e32 v85, v0, v0
	v_pk_add_f32 v[62:63], v[62:63], v[66:67]
	v_mul_f32_e32 v86, v1, v1
	v_pk_add_f32 v[60:61], v[60:61], v[60:61] op_sel:[0,1] op_sel_hi:[1,0]
	v_pk_add_f32 v[62:63], v[62:63], v[62:63] op_sel:[0,1] op_sel_hi:[1,0]
	v_mov_b32_e32 v61, v86
	v_mov_b32_e32 v63, v85
	v_pk_add_f32 v[60:61], v[62:63], v[60:61]
	s_nop 0
	v_pk_add_f32 v[58:59], v[60:61], v[58:59]
	s_nop 0
	v_add_f32_e32 v58, v58, v59
	ds_bpermute_b32 v59, v24, v58
	s_waitcnt lgkmcnt(0)
	v_add_f32_e32 v58, v58, v59
	ds_bpermute_b32 v59, v25, v58
	s_waitcnt lgkmcnt(0)
	v_add_f32_e32 v58, v58, v59
	ds_bpermute_b32 v59, v26, v58
	s_waitcnt lgkmcnt(0)
	v_add_f32_e32 v58, v58, v59
	ds_bpermute_b32 v59, v27, v58
	s_waitcnt lgkmcnt(0)
	v_add_f32_e32 v58, v58, v59
	ds_bpermute_b32 v59, v28, v58
	s_waitcnt lgkmcnt(0)
	v_add_f32_e32 v58, v58, v59
	ds_bpermute_b32 v59, v29, v58
	s_waitcnt lgkmcnt(0)
	v_add_f32_e32 v58, v58, v59
	v_fmamk_f32 v58, v58, 0x3a000000, v30
	v_mul_f32_e32 v59, 0x4f800000, v58
	v_cmp_gt_f32_e32 vcc, s4, v58
	s_nop 1
	v_cndmask_b32_e32 v58, v58, v59, vcc
	v_sqrt_f32_e32 v59, v58
	s_nop 0
	v_add_u32_e32 v60, -1, v59
	v_add_u32_e32 v61, 1, v59
	v_fma_f32 v62, -v60, v59, v58
	v_fma_f32 v63, -v61, v59, v58
	v_cmp_ge_f32_e64 s[0:1], 0, v62
	s_nop 1
	v_cndmask_b32_e64 v59, v59, v60, s[0:1]
	v_cmp_lt_f32_e64 s[0:1], 0, v63
	s_nop 1
	v_cndmask_b32_e64 v59, v59, v61, s[0:1]
	v_mul_f32_e32 v60, 0x37800000, v59
	v_cndmask_b32_e32 v59, v59, v60, vcc
	v_cmp_class_f32_e32 vcc, v58, v31
	s_nop 1
	v_cndmask_b32_e32 v58, v59, v58, vcc
	v_div_scale_f32 v59, s[0:1], v58, v58, 1.0
	v_rcp_f32_e32 v60, v59
	v_div_scale_f32 v61, vcc, 1.0, v58, 1.0
	v_fma_f32 v62, -v59, v60, 1.0
	v_fmac_f32_e32 v60, v62, v60
	v_mul_f32_e32 v62, v61, v60
	v_fma_f32 v63, -v59, v62, v61
	v_fmac_f32_e32 v62, v63, v60
	v_fma_f32 v59, -v59, v62, v61
	v_div_fmas_f32 v59, v59, v60, v62
	v_div_fixup_f32 v58, v59, v58, 1.0
	v_pk_mul_f32 v[36:37], v[58:59], v[36:37] op_sel_hi:[0,1]
	v_pk_mul_f32 v[38:39], v[58:59], v[38:39] op_sel_hi:[0,1]
	v_pk_mul_f32 v[38:39], v[38:39], v[90:91]
	v_pk_mul_f32 v[36:37], v[36:37], v[88:89]
	global_store_dwordx4 v[56:57], v[36:39], off offset:-3072
	v_pk_mul_f32 v[42:43], v[58:59], v[42:43] op_sel_hi:[0,1]
	v_pk_mul_f32 v[40:41], v[58:59], v[40:41] op_sel_hi:[0,1]
	v_pk_mul_f32 v[6:7], v[58:59], v[6:7] op_sel_hi:[0,1]
	v_pk_mul_f32 v[4:5], v[58:59], v[4:5] op_sel_hi:[0,1]
	v_pk_mul_f32 v[10:11], v[58:59], v[10:11] op_sel_hi:[0,1]
	v_pk_mul_f32 v[8:9], v[58:59], v[8:9] op_sel_hi:[0,1]
	v_pk_mul_f32 v[2:3], v[58:59], v[2:3] op_sel_hi:[0,1]
	v_pk_mul_f32 v[0:1], v[58:59], v[0:1] op_sel_hi:[0,1]
	v_pk_mul_f32 v[52:53], v[40:41], v[92:93]
	v_pk_mul_f32 v[54:55], v[42:43], v[94:95]
	global_store_dwordx4 v[56:57], v[52:55], off offset:-2048
	v_pk_mul_f32 v[40:41], v[58:59], v[46:47] op_sel_hi:[0,1]
	v_pk_mul_f32 v[42:43], v[58:59], v[44:45] op_sel_hi:[0,1]
	v_pk_mul_f32 v[36:37], v[42:43], v[96:97]
	v_pk_mul_f32 v[38:39], v[40:41], v[98:99]
	global_store_dwordx4 v[56:57], v[36:39], off offset:-1024
	v_pk_mul_f32 v[40:41], v[58:59], v[50:51] op_sel_hi:[0,1]
	v_pk_mul_f32 v[42:43], v[58:59], v[48:49] op_sel_hi:[0,1]
	v_pk_mul_f32 v[52:53], v[42:43], v[100:101]
	v_pk_mul_f32 v[54:55], v[40:41], v[102:103]
	global_store_dwordx4 v[22:23], v[52:55], off offset:-4096
	v_pk_mul_f32 v[4:5], v[4:5], v[104:105]
	v_pk_mul_f32 v[6:7], v[6:7], v[106:107]
	global_store_dwordx4 v[22:23], v[4:7], off offset:-3072
	v_pk_mul_f32 v[36:37], v[8:9], v[108:109]
	v_pk_mul_f32 v[38:39], v[10:11], v[110:111]
	global_store_dwordx4 v[22:23], v[36:39], off offset:-2048
	v_pk_mul_f32 v[8:9], v[58:59], v[34:35] op_sel_hi:[0,1]
	v_pk_mul_f32 v[10:11], v[58:59], v[32:33] op_sel_hi:[0,1]
	v_pk_mul_f32 v[52:53], v[10:11], v[112:113]
	v_pk_mul_f32 v[54:55], v[8:9], v[114:115]
	global_store_dwordx4 v[22:23], v[52:55], off offset:-1024
	v_pk_mul_f32 v[0:1], v[0:1], v[116:117]
	v_pk_mul_f32 v[2:3], v[2:3], v[118:119]
	global_store_dwordx4 v[22:23], v[0:3], off
	v_lshl_add_u64 v[22:23], v[22:23], 0, s[2:3]
	s_cbranch_scc1 .LBB0_1395
